# P0b norm_rows: gamma/scale/shift loads of column chunks 1..7 issued with chunk 0's at the top of each row (staging registers), no per-chunk waits; on top of rotary prefetch
# speedup vs baseline: 1.0127x; 1.0008x over previous
; __device__ __forceinline__ unsigned cvt_pk_bf16(float lo, float hi) { unsigned r; asm volatile("v_cvt_pk_bf16_f32 %0, %1, %2" : "=v"(r) : "v"(lo), "v"(hi)); return r; }
; __device__ __forceinline__ void norm_rows(const float* x, const float* g, const float* modl  , bf16_t* H, float* out, int mode, int gw, int NGW, int lane, bf16_t* xb = nullptr) {
;     for (int row = gw; row < MTOK; row += NGW) {
;         const f32x4* xr = (const f32x4*)(x + (size_t)row * DM) + lane;
;         f32x4 v[8]; float ss = 0.f;
; #pragma unroll
;         for (int j = 0; j < 8; ++j) { v[j] = xr[64 * j]; ss += (v[j].x * v[j].x + v[j].y * v[j].y) + (v[j].z * v[j].z + v[j].w * v[j].w); }
;         const float rstd = rsqrtf(wave_sum(ss) * (1.0f / DM) + EPS);
;         if (mode == 0) {
;             const int b = row >> 11; const float* sh = modl + (size_t)b * 6144; const float* sc = sh + 2048;
; #pragma unroll
;             for (int j = 0; j < 8; ++j) { const int col = 4 * lane + 256 * j; const f32x4 gg = *(const f32x4*)(g + col), s1 = *(const f32x4*)(sc + col), s0 = *(const f32x4*)(sh + col);
;                 const f32x4 h = v[j] * rstd * gg * (1.0f + s1) + s0; u32x2 w; w.x = cvt_pk_bf16(h.x, h.y); w.y = cvt_pk_bf16(h.z, h.w);
;                 *(u32x2*)(H + (size_t)row * DM + col) = w;
;                 if (xb) { u32x2 wx; wx.x = cvt_pk_bf16(v[j].x, v[j].y); wx.y = cvt_pk_bf16(v[j].z, v[j].w); *(u32x2*)(xb + (size_t)row * DM + col) = wx; } }
.LBB0_171:
	global_load_dwordx4 v[28:31], v[46:47], off offset:-4096
	global_load_dwordx4 v[24:27], v[46:47], off offset:-3072
	global_load_dwordx4 v[20:23], v[46:47], off offset:-2048
	global_load_dwordx4 v[12:15], v[46:47], off
	global_load_dwordx4 v[16:19], v[46:47], off offset:-1024
	global_load_dwordx4 v[8:11], v[46:47], off offset:1024
	global_load_dwordx4 v[0:3], v[46:47], off offset:3072
	global_load_dwordx4 v[4:7], v[46:47], off offset:2048
	s_ashr_i32 s6, s16, 11
	s_mul_hi_i32 s7, s6, 0x6000
	s_mulk_i32 s6, 0x6000
	s_add_u32 s24, s10, s6
	s_addc_u32 s25, s11, s7
	s_add_u32 s26, s24, 0x2000
	s_addc_u32 s27, s25, 0
	global_load_dwordx4 v[70:73], v[34:35], off
	global_load_dwordx4 v[50:53], v32, s[26:27]
	global_load_dwordx4 v[74:77], v32, s[24:25]
	v_lshl_add_u64 v[108:109], s[24:25], 0, v[32:33]
	global_load_dwordx4 v[110:113], v[34:35], off offset:1024
	global_load_dwordx4 v[114:117], v62, s[26:27]
	global_load_dwordx4 v[118:121], v[108:109], off offset:1024
	global_load_dwordx4 v[122:125], v[34:35], off offset:2048
	global_load_dwordx4 v[126:129], v63, s[26:27]
	global_load_dwordx4 v[130:133], v[108:109], off offset:2048
	global_load_dwordx4 v[134:137], v[34:35], off offset:3072
	global_load_dwordx4 v[138:141], v64, s[26:27]
	global_load_dwordx4 v[142:145], v[108:109], off offset:3072
	global_load_dwordx4 v[146:149], v[36:37], off
	global_load_dwordx4 v[150:153], v65, s[26:27]
	global_load_dwordx4 v[154:157], v65, s[24:25]
	global_load_dwordx4 v[158:161], v[38:39], off
	global_load_dwordx4 v[162:165], v66, s[26:27]
	global_load_dwordx4 v[166:169], v66, s[24:25]
	global_load_dwordx4 v[170:173], v[40:41], off
	global_load_dwordx4 v[174:177], v67, s[26:27]
	global_load_dwordx4 v[178:181], v67, s[24:25]
	global_load_dwordx4 v[182:185], v[42:43], off
	global_load_dwordx4 v[186:189], v68, s[26:27]
	global_load_dwordx4 v[190:193], v68, s[24:25]
	s_waitcnt vmcnt(31)
	v_mov_b32_e32 v78, v29
	s_waitcnt vmcnt(30)
	v_mov_b32_e32 v79, v25
	v_mov_b32_e32 v82, v31
	v_mov_b32_e32 v83, v27
	v_mov_b32_e32 v48, v28
	v_mov_b32_e32 v49, v24
	v_mov_b32_e32 v80, v30
	v_mov_b32_e32 v81, v26
	s_waitcnt vmcnt(29)
	v_pk_mul_f32 v[84:85], v[22:23], v[22:23]
	v_pk_mul_f32 v[86:87], v[20:21], v[20:21]
	v_pk_mul_f32 v[78:79], v[78:79], v[78:79]
	v_pk_mul_f32 v[82:83], v[82:83], v[82:83]
	v_pk_mov_b32 v[100:101], v[86:87], v[84:85] op_sel:[1,0]
	v_mov_b32_e32 v87, v85
	v_pk_fma_f32 v[48:49], v[48:49], v[48:49], v[78:79]
	v_pk_fma_f32 v[78:79], v[80:81], v[80:81], v[82:83]
	s_waitcnt vmcnt(27)
	v_mul_f32_e32 v88, v17, v17
	v_mul_f32_e32 v90, v19, v19
	v_pk_add_f32 v[80:81], v[100:101], v[86:87]
	v_pk_add_f32 v[48:49], v[48:49], v[78:79]
	v_mul_f32_e32 v69, v12, v12
	v_mul_f32_e32 v99, v13, v13
	v_mul_f32_e32 v102, v14, v14
	v_mul_f32_e32 v103, v15, v15
	v_pk_fma_f32 v[84:85], v[16:17], v[16:17], v[88:89] op_sel_hi:[1,1,0]
	v_pk_fma_f32 v[88:89], v[18:19], v[18:19], v[90:91] op_sel_hi:[1,1,0]
	v_pk_add_f32 v[78:79], v[80:81], v[80:81] op_sel:[0,1] op_sel_hi:[1,0]
	v_pk_add_f32 v[48:49], v[48:49], v[48:49] op_sel:[0,1] op_sel_hi:[1,0]
	s_waitcnt vmcnt(26)
	v_pk_mul_f32 v[92:93], v[10:11], v[10:11]
	v_pk_mul_f32 v[94:95], v[8:9], v[8:9]
	v_mov_b32_e32 v85, v102
	v_mov_b32_e32 v89, v103
	v_mov_b32_e32 v79, v99
	v_mov_b32_e32 v49, v69
	v_pk_mov_b32 v[90:91], v[94:95], v[92:93] op_sel:[1,0]
	v_mov_b32_e32 v95, v93
	v_pk_add_f32 v[80:81], v[84:85], v[88:89]
	v_pk_add_f32 v[48:49], v[48:49], v[78:79]
	s_waitcnt vmcnt(24)
	v_mul_f32_e32 v96, v5, v5
	v_mul_f32_e32 v98, v7, v7
	v_pk_add_f32 v[82:83], v[90:91], v[94:95]
	v_pk_add_f32 v[48:49], v[48:49], v[80:81]
	v_mul_f32_e32 v104, v0, v0
	v_mul_f32_e32 v105, v1, v1
	v_mul_f32_e32 v106, v2, v2
	v_mul_f32_e32 v107, v3, v3
	v_pk_fma_f32 v[92:93], v[4:5], v[4:5], v[96:97] op_sel_hi:[1,1,0]
	v_pk_fma_f32 v[96:97], v[6:7], v[6:7], v[98:99] op_sel_hi:[1,1,0]
	v_pk_add_f32 v[82:83], v[82:83], v[82:83] op_sel:[0,1] op_sel_hi:[1,0]
	v_pk_add_f32 v[48:49], v[48:49], v[48:49] op_sel:[0,1] op_sel_hi:[1,0]
	v_mov_b32_e32 v93, v106
	v_mov_b32_e32 v97, v107
	v_mov_b32_e32 v83, v105
	v_mov_b32_e32 v49, v104
	v_pk_add_f32 v[84:85], v[92:93], v[96:97]
	v_pk_add_f32 v[48:49], v[48:49], v[82:83]
	s_waitcnt vmcnt(22)
	v_pk_add_f32 v[50:51], v[50:51], 1.0 op_sel_hi:[1,0]
	v_pk_add_f32 v[48:49], v[48:49], v[84:85]
	s_nop 0
	v_add_f32_e32 v48, v48, v49
	ds_bpermute_b32 v49, v55, v48
	s_waitcnt lgkmcnt(0)
	v_add_f32_e32 v48, v48, v49
	ds_bpermute_b32 v49, v56, v48
	s_waitcnt lgkmcnt(0)
	v_add_f32_e32 v48, v48, v49
	ds_bpermute_b32 v49, v57, v48
	s_waitcnt lgkmcnt(0)
	v_add_f32_e32 v48, v48, v49
	ds_bpermute_b32 v49, v58, v48
	s_waitcnt lgkmcnt(0)
	v_add_f32_e32 v69, v48, v49
	ds_bpermute_b32 v78, v59, v69
	v_lshl_add_u64 v[48:49], s[18:19], 0, v[44:45]
	s_waitcnt lgkmcnt(0)
	v_add_f32_e32 v69, v69, v78
	ds_bpermute_b32 v80, v60, v69
	v_add_co_u32_e32 v78, vcc, 0xca00000, v48
	s_waitcnt lgkmcnt(0)
	v_add_f32_e32 v69, v69, v80
	v_fmamk_f32 v69, v69, 0x3a000000, v61
	v_mul_f32_e32 v80, 0x4b800000, v69
	v_cmp_gt_f32_e64 s[6:7], s3, v69
	v_addc_co_u32_e32 v79, vcc, 0, v49, vcc
	s_nop 0
	v_cndmask_b32_e64 v69, v69, v80, s[6:7]
	v_rsq_f32_e32 v69, v69
	v_pk_add_f32 v[80:81], v[52:53], 1.0 op_sel_hi:[1,0]
	s_and_b64 vcc, exec, s[4:5]
	v_mul_f32_e32 v52, 0x45800000, v69
	v_cndmask_b32_e64 v52, v69, v52, s[6:7]
	v_pk_mul_f32 v[84:85], v[28:29], v[52:53] op_sel_hi:[1,0]
	v_pk_mul_f32 v[82:83], v[30:31], v[52:53] op_sel_hi:[1,0]
	v_pk_mul_f32 v[70:71], v[70:71], v[84:85]
	v_pk_mul_f32 v[72:73], v[72:73], v[82:83]
	s_waitcnt vmcnt(0)
	v_pk_fma_f32 v[50:51], v[50:51], v[70:71], v[74:75]
	v_pk_fma_f32 v[72:73], v[80:81], v[72:73], v[76:77]
	v_cvt_pk_bf16_f32 v50, v50, v51
	s_nop 0
	v_cvt_pk_bf16_f32 v51, v72, v73
	global_store_dwordx2 v[78:79], v[50:51], off
	v_lshl_add_u64 v[50:51], s[8:9], 0, v[44:45]
	s_cbranch_vccnz .LBB0_173
	v_cvt_pk_bf16_f32 v28, v28, v29
	v_cvt_pk_bf16_f32 v29, v30, v31
	global_store_dwordx2 v[50:51], v[28:29], off
; __device__ __forceinline__ unsigned cvt_pk_bf16(float lo, float hi) { unsigned r; asm volatile("v_cvt_pk_bf16_f32 %0, %1, %2" : "=v"(r) : "v"(lo), "v"(hi)); return r; }
; __device__ __forceinline__ void norm_rows(const float* x, const float* g, const float* modl  , bf16_t* H, float* out, int mode, int gw, int NGW, int lane, bf16_t* xb = nullptr) {
;     ...
;             for (int j = 0; j < 8; ++j) { const int col = 4 * lane + 256 * j; const f32x4 gg = *(const f32x4*)(g + col), s1 = *(const f32x4*)(sc + col), s0 = *(const f32x4*)(sh + col);
;                 const f32x4 h = v[j] * rstd * gg * (1.0f + s1) + s0; u32x2 w; w.x = cvt_pk_bf16(h.x, h.y); w.y = cvt_pk_bf16(h.z, h.w);
;                 *(u32x2*)(H + (size_t)row * DM + col) = w;
;                 if (xb) { u32x2 wx; wx.x = cvt_pk_bf16(v[j].x, v[j].y); wx.y = cvt_pk_bf16(v[j].z, v[j].w); *(u32x2*)(xb + (size_t)row * DM + col) = wx; } }
.LBB0_173:
	v_mov_b32_e32 v70, v110
	v_mov_b32_e32 v71, v111
	v_mov_b32_e32 v72, v112
	v_mov_b32_e32 v73, v113
	v_mov_b32_e32 v74, v114
	v_mov_b32_e32 v75, v115
	v_mov_b32_e32 v76, v116
	v_mov_b32_e32 v77, v117
	v_lshl_add_u64 v[28:29], s[24:25], 0, v[32:33]
	v_mov_b32_e32 v78, v118
	v_mov_b32_e32 v79, v119
	v_mov_b32_e32 v80, v120
	v_mov_b32_e32 v81, v121
	v_mov_b32_e32 v53, v52
	v_mov_b32_e32 v30, v52
	v_mov_b32_e32 v31, v52
	v_add_co_u32_e32 v82, vcc, 0xca00000, v48
	v_pk_mul_f32 v[86:87], v[24:25], v[52:53]
	v_pk_mul_f32 v[84:85], v[26:27], v[30:31]
	v_addc_co_u32_e32 v83, vcc, 0, v49, vcc
	s_and_b64 vcc, exec, s[4:5]
	v_pk_mul_f32 v[70:71], v[86:87], v[70:71]
	v_pk_add_f32 v[74:75], v[74:75], 1.0 op_sel_hi:[1,0]
	v_pk_mul_f32 v[72:73], v[84:85], v[72:73]
	v_pk_add_f32 v[76:77], v[76:77], 1.0 op_sel_hi:[1,0]
	v_pk_fma_f32 v[70:71], v[70:71], v[74:75], v[78:79]
	v_pk_fma_f32 v[72:73], v[72:73], v[76:77], v[80:81]
	v_cvt_pk_bf16_f32 v70, v70, v71
	s_nop 0
	v_cvt_pk_bf16_f32 v71, v72, v73
	global_store_dwordx2 v[82:83], v[70:71], off offset:512
	s_cbranch_vccnz .LBB0_175
	v_cvt_pk_bf16_f32 v24, v24, v25
	v_cvt_pk_bf16_f32 v25, v26, v27
	global_store_dwordx2 v[50:51], v[24:25], off offset:512
.LBB0_175:
	v_mov_b32_e32 v24, v122
	v_mov_b32_e32 v25, v123
	v_mov_b32_e32 v26, v124
	v_mov_b32_e32 v27, v125
	s_nop 0
	v_mov_b32_e32 v70, v126
	v_mov_b32_e32 v71, v127
	v_mov_b32_e32 v72, v128
	v_mov_b32_e32 v73, v129
	v_mov_b32_e32 v74, v130
	v_mov_b32_e32 v75, v131
	v_mov_b32_e32 v76, v132
	v_mov_b32_e32 v77, v133
	v_pk_mul_f32 v[78:79], v[20:21], v[52:53]
	v_add_co_u32_e32 v80, vcc, 0xca00000, v48
	v_pk_mul_f32 v[30:31], v[22:23], v[30:31]
	s_nop 0
	v_addc_co_u32_e32 v81, vcc, 0, v49, vcc
	s_and_b64 vcc, exec, s[4:5]
	v_pk_mul_f32 v[24:25], v[78:79], v[24:25]
	v_pk_add_f32 v[70:71], v[70:71], 1.0 op_sel_hi:[1,0]
	v_pk_mul_f32 v[26:27], v[30:31], v[26:27]
	v_pk_add_f32 v[30:31], v[72:73], 1.0 op_sel_hi:[1,0]
	v_pk_fma_f32 v[24:25], v[24:25], v[70:71], v[74:75]
	v_pk_fma_f32 v[26:27], v[26:27], v[30:31], v[76:77]
	v_cvt_pk_bf16_f32 v24, v24, v25
	s_nop 0
	v_cvt_pk_bf16_f32 v25, v26, v27
	global_store_dwordx2 v[80:81], v[24:25], off offset:1024
	s_cbranch_vccnz .LBB0_177
	v_cvt_pk_bf16_f32 v20, v20, v21
	v_cvt_pk_bf16_f32 v21, v22, v23
	global_store_dwordx2 v[50:51], v[20:21], off offset:1024
.LBB0_177:
	v_mov_b32_e32 v22, v134
	v_mov_b32_e32 v23, v135
	v_mov_b32_e32 v24, v136
	v_mov_b32_e32 v25, v137
	v_mov_b32_e32 v70, v138
	v_mov_b32_e32 v71, v139
	v_mov_b32_e32 v72, v140
	v_mov_b32_e32 v73, v141
	v_mov_b32_e32 v74, v142
	v_mov_b32_e32 v75, v143
	v_mov_b32_e32 v76, v144
	v_mov_b32_e32 v77, v145
	v_mov_b32_e32 v20, v52
	v_mov_b32_e32 v21, v52
	v_pk_mul_f32 v[26:27], v[16:17], v[52:53]
	v_add_co_u32_e32 v28, vcc, 0xca00000, v48
	v_pk_mul_f32 v[30:31], v[18:19], v[20:21]
	s_nop 0
	v_addc_co_u32_e32 v29, vcc, 0, v49, vcc
	s_and_b64 vcc, exec, s[4:5]
	v_pk_mul_f32 v[24:25], v[30:31], v[24:25]
	v_pk_mul_f32 v[22:23], v[26:27], v[22:23]
	v_pk_add_f32 v[30:31], v[70:71], 1.0 op_sel_hi:[1,0]
	v_pk_add_f32 v[26:27], v[72:73], 1.0 op_sel_hi:[1,0]
	v_pk_fma_f32 v[22:23], v[22:23], v[30:31], v[74:75]
	v_pk_fma_f32 v[24:25], v[24:25], v[26:27], v[76:77]
	v_cvt_pk_bf16_f32 v22, v22, v23
	s_nop 0
	v_cvt_pk_bf16_f32 v23, v24, v25
	global_store_dwordx2 v[28:29], v[22:23], off offset:1536
	s_cbranch_vccnz .LBB0_179
	v_cvt_pk_bf16_f32 v16, v16, v17
	v_cvt_pk_bf16_f32 v17, v18, v19
	global_store_dwordx2 v[50:51], v[16:17], off offset:1536
; __device__ __forceinline__ unsigned cvt_pk_bf16(float lo, float hi) { unsigned r; asm volatile("v_cvt_pk_bf16_f32 %0, %1, %2" : "=v"(r) : "v"(lo), "v"(hi)); return r; }
; __device__ __forceinline__ void norm_rows(const float* x, const float* g, const float* modl  , bf16_t* H, float* out, int mode, int gw, int NGW, int lane, bf16_t* xb = nullptr) {
;     ...
;             for (int j = 0; j < 8; ++j) { const int col = 4 * lane + 256 * j; const f32x4 gg = *(const f32x4*)(g + col), s1 = *(const f32x4*)(sc + col), s0 = *(const f32x4*)(sh + col);
;                 const f32x4 h = v[j] * rstd * gg * (1.0f + s1) + s0; u32x2 w; w.x = cvt_pk_bf16(h.x, h.y); w.y = cvt_pk_bf16(h.z, h.w);
;                 *(u32x2*)(H + (size_t)row * DM + col) = w;
;                 if (xb) { u32x2 wx; wx.x = cvt_pk_bf16(v[j].x, v[j].y); wx.y = cvt_pk_bf16(v[j].z, v[j].w); *(u32x2*)(xb + (size_t)row * DM + col) = wx; } }
.LBB0_179:
	v_mov_b32_e32 v16, v146
	v_mov_b32_e32 v17, v147
	v_mov_b32_e32 v18, v148
	v_mov_b32_e32 v19, v149
	s_nop 0
	v_mov_b32_e32 v22, v150
	v_mov_b32_e32 v23, v151
	v_mov_b32_e32 v24, v152
	v_mov_b32_e32 v25, v153
	v_mov_b32_e32 v26, v154
	v_mov_b32_e32 v27, v155
	v_mov_b32_e32 v28, v156
	v_mov_b32_e32 v29, v157
	v_pk_mul_f32 v[30:31], v[12:13], v[52:53]
	v_add_co_u32_e32 v70, vcc, 0xca00000, v48
	v_pk_mul_f32 v[20:21], v[14:15], v[20:21]
	s_nop 0
	v_addc_co_u32_e32 v71, vcc, 0, v49, vcc
	s_and_b64 vcc, exec, s[4:5]
	v_pk_mul_f32 v[16:17], v[30:31], v[16:17]
	v_pk_add_f32 v[22:23], v[22:23], 1.0 op_sel_hi:[1,0]
	v_pk_mul_f32 v[18:19], v[20:21], v[18:19]
	v_pk_add_f32 v[20:21], v[24:25], 1.0 op_sel_hi:[1,0]
	v_pk_fma_f32 v[16:17], v[16:17], v[22:23], v[26:27]
	v_pk_fma_f32 v[18:19], v[18:19], v[20:21], v[28:29]
	v_cvt_pk_bf16_f32 v16, v16, v17
	s_nop 0
	v_cvt_pk_bf16_f32 v17, v18, v19
	global_store_dwordx2 v[70:71], v[16:17], off offset:2048
	s_cbranch_vccnz .LBB0_181
	v_cvt_pk_bf16_f32 v12, v12, v13
	v_cvt_pk_bf16_f32 v13, v14, v15
	global_store_dwordx2 v[50:51], v[12:13], off offset:2048
.LBB0_181:
	v_mov_b32_e32 v14, v158
	v_mov_b32_e32 v15, v159
	v_mov_b32_e32 v16, v160
	v_mov_b32_e32 v17, v161
	v_mov_b32_e32 v18, v162
	v_mov_b32_e32 v19, v163
	v_mov_b32_e32 v20, v164
	v_mov_b32_e32 v21, v165
	v_mov_b32_e32 v22, v166
	v_mov_b32_e32 v23, v167
	v_mov_b32_e32 v24, v168
	v_mov_b32_e32 v25, v169
	v_mov_b32_e32 v12, v52
	v_mov_b32_e32 v13, v52
	v_pk_mul_f32 v[26:27], v[8:9], v[52:53]
	v_add_co_u32_e32 v28, vcc, 0xca00000, v48
	v_pk_mul_f32 v[30:31], v[10:11], v[12:13]
	s_nop 0
	v_addc_co_u32_e32 v29, vcc, 0, v49, vcc
	s_and_b64 vcc, exec, s[4:5]
	v_pk_mul_f32 v[14:15], v[26:27], v[14:15]
	v_pk_add_f32 v[18:19], v[18:19], 1.0 op_sel_hi:[1,0]
	v_pk_mul_f32 v[16:17], v[30:31], v[16:17]
	v_pk_add_f32 v[20:21], v[20:21], 1.0 op_sel_hi:[1,0]
	v_pk_fma_f32 v[14:15], v[14:15], v[18:19], v[22:23]
	v_pk_fma_f32 v[16:17], v[16:17], v[20:21], v[24:25]
	v_cvt_pk_bf16_f32 v14, v14, v15
	s_nop 0
	v_cvt_pk_bf16_f32 v15, v16, v17
	global_store_dwordx2 v[28:29], v[14:15], off offset:2560
	s_cbranch_vccnz .LBB0_183
	v_cvt_pk_bf16_f32 v8, v8, v9
	v_cvt_pk_bf16_f32 v9, v10, v11
	global_store_dwordx2 v[50:51], v[8:9], off offset:2560
.LBB0_183:
	v_mov_b32_e32 v8, v170
	v_mov_b32_e32 v9, v171
	v_mov_b32_e32 v10, v172
	v_mov_b32_e32 v11, v173
	s_nop 0
	v_mov_b32_e32 v14, v174
	v_mov_b32_e32 v15, v175
	v_mov_b32_e32 v16, v176
	v_mov_b32_e32 v17, v177
	v_mov_b32_e32 v18, v178
	v_mov_b32_e32 v19, v179
	v_mov_b32_e32 v20, v180
	v_mov_b32_e32 v21, v181
	v_pk_mul_f32 v[22:23], v[4:5], v[52:53]
	v_add_co_u32_e32 v24, vcc, 0xca00000, v48
	v_pk_mul_f32 v[12:13], v[6:7], v[12:13]
	s_nop 0
	v_addc_co_u32_e32 v25, vcc, 0, v49, vcc
	s_and_b64 vcc, exec, s[4:5]
	v_pk_mul_f32 v[8:9], v[22:23], v[8:9]
	v_pk_add_f32 v[14:15], v[14:15], 1.0 op_sel_hi:[1,0]
	v_pk_mul_f32 v[10:11], v[12:13], v[10:11]
	v_pk_add_f32 v[12:13], v[16:17], 1.0 op_sel_hi:[1,0]
	v_pk_fma_f32 v[8:9], v[8:9], v[14:15], v[18:19]
	v_pk_fma_f32 v[10:11], v[10:11], v[12:13], v[20:21]
	v_cvt_pk_bf16_f32 v8, v8, v9
	s_nop 0
	v_cvt_pk_bf16_f32 v9, v10, v11
	global_store_dwordx2 v[24:25], v[8:9], off offset:3072
	s_cbranch_vccnz .LBB0_185
	v_cvt_pk_bf16_f32 v4, v4, v5
	v_cvt_pk_bf16_f32 v5, v6, v7
	global_store_dwordx2 v[50:51], v[4:5], off offset:3072
.LBB0_185:
	v_mov_b32_e32 v4, v182
	v_mov_b32_e32 v5, v183
	v_mov_b32_e32 v6, v184
	v_mov_b32_e32 v7, v185
	s_nop 0
	v_mov_b32_e32 v8, v186
	v_mov_b32_e32 v9, v187
	v_mov_b32_e32 v10, v188
	v_mov_b32_e32 v11, v189
	v_mov_b32_e32 v12, v190
	v_mov_b32_e32 v13, v191
	v_mov_b32_e32 v14, v192
	v_mov_b32_e32 v15, v193
	v_mov_b32_e32 v16, v52
	v_mov_b32_e32 v17, v52
	v_pk_mul_f32 v[18:19], v[0:1], v[52:53]
	v_add_co_u32_e32 v20, vcc, 0xca00000, v48
	v_pk_mul_f32 v[16:17], v[2:3], v[16:17]
	s_nop 0
	v_addc_co_u32_e32 v21, vcc, 0, v49, vcc
	s_and_b64 vcc, exec, s[4:5]
	v_pk_mul_f32 v[4:5], v[18:19], v[4:5]
	v_pk_add_f32 v[8:9], v[8:9], 1.0 op_sel_hi:[1,0]
	v_pk_mul_f32 v[6:7], v[16:17], v[6:7]
	v_pk_add_f32 v[10:11], v[10:11], 1.0 op_sel_hi:[1,0]
	v_pk_fma_f32 v[4:5], v[4:5], v[8:9], v[12:13]
	v_pk_fma_f32 v[6:7], v[6:7], v[10:11], v[14:15]
	v_cvt_pk_bf16_f32 v4, v4, v5
	s_nop 0
	v_cvt_pk_bf16_f32 v5, v6, v7
	global_store_dwordx2 v[20:21], v[4:5], off offset:3584
	s_cbranch_vccnz .LBB0_170
	v_cvt_pk_bf16_f32 v0, v0, v1
	v_cvt_pk_bf16_f32 v1, v2, v3
	global_store_dwordx2 v[50:51], v[0:1], off offset:3584
	s_branch .LBB0_170
